# streaming-store hint: nt on new_k/new_v f32 output stores (write-once outputs, avoid L2 pollution)
# speedup vs baseline: 1.0015x; 1.0002x over previous
.LBB0_202:
	s_or_b64 exec, exec, s[54:55]
	s_lshr_b32 s13, s12, 6
	s_or_b32 s13, s13, s86
	v_lshlrev_b32_e32 v198, 3, v148
	s_lshl_b32 s23, s13, 8
	v_cmp_gt_i32_e32 vcc, s22, v152
	v_lshl_add_u64 v[156:157], s[6:7], 0, v[198:199]
	v_or_b32_e32 v144, s23, v167
	v_cndmask_b32_e32 v154, 1.0, v249, vcc
	v_lshlrev_b32_e32 v151, 2, v148
	v_and_b32_e32 v161, 64, v149
	v_mad_i64_i32 v[164:165], s[54:55], v150, s62, v[156:157]
	v_ashrrev_i32_e32 v145, 31, v144
	v_ashrrev_i32_e32 v153, 31, v152
	v_pk_mul_f32 v[146:147], v[154:155], v[60:61] op_sel_hi:[0,1]
	v_pk_mul_f32 v[148:149], v[154:155], v[62:63] op_sel_hi:[0,1]
	v_lshlrev_b64 v[162:163], 9, v[144:145]
	v_lshl_add_u64 v[144:145], v[152:153], 1, v[164:165]
	v_cvt_pk_bf16_f32 v146, v146, v147
	v_cvt_pk_bf16_f32 v147, v148, v149
	ds_write_b64 v200, v[146:147]
	v_pk_mul_f32 v[146:147], v[154:155], v[52:53] op_sel_hi:[0,1]
	v_pk_mul_f32 v[148:149], v[154:155], v[54:55] op_sel_hi:[0,1]
	v_cvt_pk_bf16_f32 v146, v146, v147
	v_cvt_pk_bf16_f32 v147, v148, v149
	ds_write_b64 v200, v[146:147] offset:32
	v_pk_mul_f32 v[146:147], v[154:155], v[56:57] op_sel_hi:[0,1]
	v_pk_mul_f32 v[148:149], v[154:155], v[58:59] op_sel_hi:[0,1]
	v_cvt_pk_bf16_f32 v146, v146, v147
	v_cvt_pk_bf16_f32 v147, v148, v149
	ds_write_b64 v200, v[146:147] offset:64
	v_pk_mul_f32 v[146:147], v[154:155], v[48:49] op_sel_hi:[0,1]
	v_pk_mul_f32 v[148:149], v[154:155], v[50:51] op_sel_hi:[0,1]
	v_cvt_pk_bf16_f32 v146, v146, v147
	v_cvt_pk_bf16_f32 v147, v148, v149
	ds_write_b64 v200, v[146:147] offset:96
	s_waitcnt lgkmcnt(0)
	ds_read_b128 v[204:207], v201
	ds_read_b128 v[208:211], v201 offset:1152
	v_lshl_add_u64 v[212:213], v[144:145], 0, v[202:203]
	v_lshl_add_u64 v[214:215], v[212:213], 0, s[100:101]
	s_waitcnt lgkmcnt(0)
	global_store_dwordx4 v[212:213], v[204:207], off sc1
	global_store_dwordx4 v[214:215], v[208:211], off sc1
	v_and_b32_e32 v144, 0xffffff00, v152
	v_cmp_eq_u32_e32 vcc, s22, v144
	s_xor_b64 s[54:55], s[52:53], -1
	s_and_b64 s[92:93], s[54:55], vcc
	v_and_b32_e32 v168, 0x280, v152
	v_lshlrev_b32_e32 v150, 2, v161
	v_lshlrev_b32_e32 v148, 2, v151
	s_and_saveexec_b64 s[94:95], s[92:93]
	s_cbranch_execz .LBB0_204
	v_cmp_eq_u32_e32 vcc, s18, v168
	v_mov_b32_e32 v151, v199
	v_mov_b32_e32 v149, v199
	v_cndmask_b32_e32 v198, 0, v250, vcc
	v_lshl_add_u64 v[144:145], s[34:35], 0, v[198:199]
	v_lshl_add_u64 v[144:145], v[144:145], 0, v[162:163]
	v_lshl_add_u64 v[144:145], v[144:145], 0, v[150:151]
	v_lshl_add_u64 v[144:145], v[144:145], 0, v[148:149]
	ds_write_b128 v216, v[60:63]
	ds_write_b128 v216, v[52:55] offset:64
	ds_write_b128 v216, v[56:59] offset:128
	ds_write_b128 v216, v[48:51] offset:192
	ds_read_b128 v[220:223], v217
	ds_read_b128 v[224:227], v217 offset:1088
	ds_read_b128 v[228:231], v217 offset:2176
	ds_read_b128 v[232:235], v217 offset:3264
	v_lshl_add_u64 v[242:243], v[144:145], 0, v[238:239]
	v_lshl_add_u64 v[218:219], v[144:145], 0, v[236:237]
	s_waitcnt lgkmcnt(0)
	global_store_dwordx4 v[218:219], v[220:223], off nt
	global_store_dwordx4 v[218:219], v[224:227], off offset:2048 nt
	global_store_dwordx4 v[242:243], v[228:231], off nt
	global_store_dwordx4 v[242:243], v[232:235], off offset:2048 nt

.LBB0_206:
	s_or_b64 exec, exec, s[52:53]
	v_cmp_gt_i32_e32 vcc, s22, v137
	s_ashr_i32 s89, s88, 31
	v_ashrrev_i32_e32 v159, 31, v158
	v_cndmask_b32_e32 v136, 1.0, v249, vcc
	v_lshl_add_u64 v[138:139], v[158:159], 0, s[88:89]
	v_lshl_add_u64 v[158:159], v[138:139], 1, v[164:165]
	v_pk_mul_f32 v[160:161], v[136:137], v[144:145] op_sel_hi:[0,1]
	v_pk_mul_f32 v[164:165], v[136:137], v[146:147] op_sel_hi:[0,1]
	v_cvt_pk_bf16_f32 v160, v160, v161
	v_cvt_pk_bf16_f32 v161, v164, v165
	ds_write_b64 v200, v[160:161]
	v_pk_mul_f32 v[160:161], v[136:137], v[140:141] op_sel_hi:[0,1]
	v_pk_mul_f32 v[164:165], v[136:137], v[142:143] op_sel_hi:[0,1]
	v_cvt_pk_bf16_f32 v160, v160, v161
	v_cvt_pk_bf16_f32 v161, v164, v165
	ds_write_b64 v200, v[160:161] offset:32
	v_pk_mul_f32 v[160:161], v[136:137], v[132:133] op_sel_hi:[0,1]
	v_pk_mul_f32 v[164:165], v[136:137], v[134:135] op_sel_hi:[0,1]
	v_cvt_pk_bf16_f32 v160, v160, v161
	v_cvt_pk_bf16_f32 v161, v164, v165
	ds_write_b64 v200, v[160:161] offset:64
	v_pk_mul_f32 v[160:161], v[136:137], v[128:129] op_sel_hi:[0,1]
	v_pk_mul_f32 v[164:165], v[136:137], v[130:131] op_sel_hi:[0,1]
	v_and_b32_e32 v149, 0xffffff00, v137
	v_cvt_pk_bf16_f32 v160, v160, v161
	v_cvt_pk_bf16_f32 v161, v164, v165
	v_cmp_eq_u32_e32 vcc, s22, v149
	ds_write_b64 v200, v[160:161] offset:96
	s_waitcnt lgkmcnt(0)
	ds_read_b128 v[204:207], v201
	ds_read_b128 v[208:211], v201 offset:1152
	v_lshl_add_u64 v[212:213], v[158:159], 0, v[202:203]
	v_lshl_add_u64 v[214:215], v[212:213], 0, s[100:101]
	s_waitcnt lgkmcnt(0)
	global_store_dwordx4 v[212:213], v[204:207], off offset:256 sc1
	global_store_dwordx4 v[214:215], v[208:211], off offset:256 sc1
	s_and_b64 s[88:89], s[54:55], vcc
	v_and_b32_e32 v158, 0x280, v137
	s_and_saveexec_b64 s[52:53], s[88:89]
	s_cbranch_execz .LBB0_208
	v_cmp_eq_u32_e32 vcc, s18, v158
	v_mov_b32_e32 v151, v199
	v_mov_b32_e32 v149, v199
	v_cndmask_b32_e32 v198, 0, v250, vcc
	v_lshl_add_u64 v[160:161], s[34:35], 0, v[198:199]
	v_lshl_add_u64 v[160:161], v[160:161], 0, v[162:163]
	v_lshl_add_u64 v[160:161], v[160:161], 0, v[150:151]
	v_lshl_add_u64 v[160:161], v[160:161], 0, v[148:149]
	ds_write_b128 v216, v[144:147]
	ds_write_b128 v216, v[140:143] offset:64
	ds_write_b128 v216, v[132:135] offset:128
	ds_write_b128 v216, v[128:131] offset:192
	ds_read_b128 v[220:223], v217
	ds_read_b128 v[224:227], v217 offset:1088
	ds_read_b128 v[228:231], v217 offset:2176
	ds_read_b128 v[232:235], v217 offset:3264
	v_lshl_add_u64 v[242:243], v[160:161], 0, v[238:239]
	v_lshl_add_u64 v[218:219], v[160:161], 0, v[236:237]
	s_waitcnt lgkmcnt(0)
	global_store_dwordx4 v[218:219], v[220:223], off nt
	global_store_dwordx4 v[218:219], v[224:227], off offset:2048 nt
	global_store_dwordx4 v[242:243], v[228:231], off nt
	global_store_dwordx4 v[242:243], v[232:235], off offset:2048 nt

.LBB0_210:
	s_or_b64 exec, exec, s[52:53]
	v_mov_b32_e32 v155, v154
	v_mad_i64_i32 v[126:127], s[52:53], v137, s62, v[156:157]
	v_pk_mul_f32 v[142:143], v[154:155], v[128:129]
	v_pk_mul_f32 v[144:145], v[154:155], v[130:131]
	v_lshl_add_u64 v[140:141], v[152:153], 1, v[126:127]
	v_cvt_pk_bf16_f32 v142, v142, v143
	v_cvt_pk_bf16_f32 v143, v144, v145
	ds_write_b64 v200, v[142:143]
	v_pk_mul_f32 v[142:143], v[154:155], v[120:121]
	v_pk_mul_f32 v[144:145], v[154:155], v[122:123]
	v_cvt_pk_bf16_f32 v142, v142, v143
	v_cvt_pk_bf16_f32 v143, v144, v145
	ds_write_b64 v200, v[142:143] offset:32
	v_pk_mul_f32 v[142:143], v[154:155], v[116:117]
	v_pk_mul_f32 v[144:145], v[154:155], v[118:119]
	v_or_b32_e32 v124, s23, v133
	v_cvt_pk_bf16_f32 v142, v142, v143
	v_cvt_pk_bf16_f32 v143, v144, v145
	v_ashrrev_i32_e32 v125, 31, v124
	ds_write_b64 v200, v[142:143] offset:64
	v_pk_mul_f32 v[142:143], v[154:155], v[112:113]
	v_pk_mul_f32 v[144:145], v[154:155], v[114:115]
	v_lshlrev_b64 v[124:125], 9, v[124:125]
	v_cvt_pk_bf16_f32 v142, v142, v143
	v_cvt_pk_bf16_f32 v143, v144, v145
	ds_write_b64 v200, v[142:143] offset:96
	s_waitcnt lgkmcnt(0)
	ds_read_b128 v[204:207], v201
	ds_read_b128 v[208:211], v201 offset:1152
	v_lshl_add_u64 v[212:213], v[140:141], 0, v[202:203]
	v_lshl_add_u64 v[214:215], v[212:213], 0, s[100:101]
	s_waitcnt lgkmcnt(0)
	global_store_dwordx4 v[212:213], v[204:207], off sc1
	global_store_dwordx4 v[214:215], v[208:211], off sc1
	s_and_saveexec_b64 s[52:53], s[92:93]
	s_cbranch_execz .LBB0_212
	v_cmp_eq_u32_e32 vcc, s18, v168
	v_mov_b32_e32 v151, v199
	v_mov_b32_e32 v149, v199
	v_cndmask_b32_e32 v198, 0, v250, vcc
	v_lshl_add_u64 v[140:141], s[34:35], 0, v[198:199]
	v_lshl_add_u64 v[140:141], v[140:141], 0, v[124:125]
	v_lshl_add_u64 v[140:141], v[140:141], 0, v[150:151]
	v_lshl_add_u64 v[140:141], v[140:141], 0, v[148:149]
	ds_write_b128 v216, v[128:131]
	ds_write_b128 v216, v[120:123] offset:64
	ds_write_b128 v216, v[116:119] offset:128
	ds_write_b128 v216, v[112:115] offset:192
	ds_read_b128 v[220:223], v217
	ds_read_b128 v[224:227], v217 offset:1088
	ds_read_b128 v[228:231], v217 offset:2176
	ds_read_b128 v[232:235], v217 offset:3264
	v_lshl_add_u64 v[242:243], v[140:141], 0, v[238:239]
	v_lshl_add_u64 v[218:219], v[140:141], 0, v[236:237]
	s_waitcnt lgkmcnt(0)
	global_store_dwordx4 v[218:219], v[220:223], off nt
	global_store_dwordx4 v[218:219], v[224:227], off offset:2048 nt
	global_store_dwordx4 v[242:243], v[228:231], off nt
	global_store_dwordx4 v[242:243], v[232:235], off offset:2048 nt

.LBB0_214:
	s_or_b64 exec, exec, s[52:53]
	v_mov_b32_e32 v137, v136
	v_pk_mul_f32 v[110:111], v[136:137], v[112:113]
	v_pk_mul_f32 v[116:117], v[136:137], v[114:115]
	v_lshl_add_u64 v[108:109], v[138:139], 1, v[126:127]
	v_cvt_pk_bf16_f32 v110, v110, v111
	v_cvt_pk_bf16_f32 v111, v116, v117
	ds_write_b64 v200, v[110:111]
	v_pk_mul_f32 v[110:111], v[136:137], v[104:105]
	v_pk_mul_f32 v[116:117], v[136:137], v[106:107]
	v_cvt_pk_bf16_f32 v110, v110, v111
	v_cvt_pk_bf16_f32 v111, v116, v117
	ds_write_b64 v200, v[110:111] offset:32
	v_pk_mul_f32 v[110:111], v[136:137], v[100:101]
	v_pk_mul_f32 v[116:117], v[136:137], v[102:103]
	v_cvt_pk_bf16_f32 v110, v110, v111
	v_cvt_pk_bf16_f32 v111, v116, v117
	ds_write_b64 v200, v[110:111] offset:64
	v_pk_mul_f32 v[110:111], v[136:137], v[96:97]
	v_pk_mul_f32 v[116:117], v[136:137], v[98:99]
	v_cvt_pk_bf16_f32 v110, v110, v111
	v_cvt_pk_bf16_f32 v111, v116, v117
	ds_write_b64 v200, v[110:111] offset:96
	s_waitcnt lgkmcnt(0)
	ds_read_b128 v[204:207], v201
	ds_read_b128 v[208:211], v201 offset:1152
	v_lshl_add_u64 v[212:213], v[108:109], 0, v[202:203]
	v_lshl_add_u64 v[214:215], v[212:213], 0, s[100:101]
	s_waitcnt lgkmcnt(0)
	global_store_dwordx4 v[212:213], v[204:207], off offset:256 sc1
	global_store_dwordx4 v[214:215], v[208:211], off offset:256 sc1
	s_and_saveexec_b64 s[52:53], s[88:89]
	s_cbranch_execz .LBB0_216
	v_cmp_eq_u32_e32 vcc, s18, v158
	v_mov_b32_e32 v151, v199
	v_mov_b32_e32 v149, v199
	v_cndmask_b32_e32 v198, 0, v250, vcc
	v_lshl_add_u64 v[108:109], s[34:35], 0, v[198:199]
	v_lshl_add_u64 v[108:109], v[108:109], 0, v[124:125]
	v_lshl_add_u64 v[108:109], v[108:109], 0, v[150:151]
	v_lshl_add_u64 v[108:109], v[108:109], 0, v[148:149]
	ds_write_b128 v216, v[112:115]
	ds_write_b128 v216, v[104:107] offset:64
	ds_write_b128 v216, v[100:103] offset:128
	ds_write_b128 v216, v[96:99] offset:192
	ds_read_b128 v[220:223], v217
	ds_read_b128 v[224:227], v217 offset:1088
	ds_read_b128 v[228:231], v217 offset:2176
	ds_read_b128 v[232:235], v217 offset:3264
	v_lshl_add_u64 v[242:243], v[108:109], 0, v[238:239]
	v_lshl_add_u64 v[218:219], v[108:109], 0, v[236:237]
	s_waitcnt lgkmcnt(0)
	global_store_dwordx4 v[218:219], v[220:223], off nt
	global_store_dwordx4 v[218:219], v[224:227], off offset:2048 nt
	global_store_dwordx4 v[242:243], v[228:231], off nt
	global_store_dwordx4 v[242:243], v[232:235], off offset:2048 nt

.LBB0_218:
	s_or_b64 exec, exec, s[52:53]
	v_mad_i64_i32 v[94:95], s[52:53], v103, s62, v[156:157]
	v_pk_mul_f32 v[106:107], v[154:155], v[96:97]
	v_pk_mul_f32 v[108:109], v[154:155], v[98:99]
	v_lshl_add_u64 v[104:105], v[152:153], 1, v[94:95]
	v_cvt_pk_bf16_f32 v106, v106, v107
	v_cvt_pk_bf16_f32 v107, v108, v109
	ds_write_b64 v200, v[106:107]
	v_pk_mul_f32 v[106:107], v[154:155], v[88:89]
	v_pk_mul_f32 v[108:109], v[154:155], v[90:91]
	v_cvt_pk_bf16_f32 v106, v106, v107
	v_cvt_pk_bf16_f32 v107, v108, v109
	ds_write_b64 v200, v[106:107] offset:32
	v_pk_mul_f32 v[106:107], v[154:155], v[84:85]
	v_pk_mul_f32 v[108:109], v[154:155], v[86:87]
	v_or_b32_e32 v92, s23, v101
	v_cvt_pk_bf16_f32 v106, v106, v107
	v_cvt_pk_bf16_f32 v107, v108, v109
	v_ashrrev_i32_e32 v93, 31, v92
	ds_write_b64 v200, v[106:107] offset:64
	v_pk_mul_f32 v[106:107], v[154:155], v[80:81]
	v_pk_mul_f32 v[108:109], v[154:155], v[82:83]
	v_lshlrev_b64 v[92:93], 9, v[92:93]
	v_cvt_pk_bf16_f32 v106, v106, v107
	v_cvt_pk_bf16_f32 v107, v108, v109
	ds_write_b64 v200, v[106:107] offset:96
	s_waitcnt lgkmcnt(0)
	ds_read_b128 v[204:207], v201
	ds_read_b128 v[208:211], v201 offset:1152
	v_lshl_add_u64 v[212:213], v[104:105], 0, v[202:203]
	v_lshl_add_u64 v[214:215], v[212:213], 0, s[100:101]
	s_waitcnt lgkmcnt(0)
	global_store_dwordx4 v[212:213], v[204:207], off sc1
	global_store_dwordx4 v[214:215], v[208:211], off sc1
	s_and_saveexec_b64 s[52:53], s[92:93]
	s_cbranch_execz .LBB0_220
	v_cmp_eq_u32_e32 vcc, s18, v168
	v_mov_b32_e32 v151, v199
	v_mov_b32_e32 v149, v199
	v_cndmask_b32_e32 v198, 0, v250, vcc
	v_lshl_add_u64 v[104:105], s[34:35], 0, v[198:199]
	v_lshl_add_u64 v[104:105], v[104:105], 0, v[92:93]
	v_lshl_add_u64 v[104:105], v[104:105], 0, v[150:151]
	v_lshl_add_u64 v[104:105], v[104:105], 0, v[148:149]
	ds_write_b128 v216, v[96:99]
	ds_write_b128 v216, v[88:91] offset:64
	ds_write_b128 v216, v[84:87] offset:128
	ds_write_b128 v216, v[80:83] offset:192
	ds_read_b128 v[220:223], v217
	ds_read_b128 v[224:227], v217 offset:1088
	ds_read_b128 v[228:231], v217 offset:2176
	ds_read_b128 v[232:235], v217 offset:3264
	v_lshl_add_u64 v[242:243], v[104:105], 0, v[238:239]
	v_lshl_add_u64 v[218:219], v[104:105], 0, v[236:237]
	s_waitcnt lgkmcnt(0)
	global_store_dwordx4 v[218:219], v[220:223], off nt
	global_store_dwordx4 v[218:219], v[224:227], off offset:2048 nt
	global_store_dwordx4 v[242:243], v[228:231], off nt
	global_store_dwordx4 v[242:243], v[232:235], off offset:2048 nt

.LBB0_222:
	s_or_b64 exec, exec, s[52:53]
	v_pk_mul_f32 v[78:79], v[136:137], v[80:81]
	v_pk_mul_f32 v[84:85], v[136:137], v[82:83]
	v_lshl_add_u64 v[76:77], v[138:139], 1, v[94:95]
	v_cvt_pk_bf16_f32 v78, v78, v79
	v_cvt_pk_bf16_f32 v79, v84, v85
	ds_write_b64 v200, v[78:79]
	v_pk_mul_f32 v[78:79], v[136:137], v[72:73]
	v_pk_mul_f32 v[84:85], v[136:137], v[74:75]
	v_cvt_pk_bf16_f32 v78, v78, v79
	v_cvt_pk_bf16_f32 v79, v84, v85
	ds_write_b64 v200, v[78:79] offset:32
	v_pk_mul_f32 v[78:79], v[136:137], v[68:69]
	v_pk_mul_f32 v[84:85], v[136:137], v[70:71]
	v_cvt_pk_bf16_f32 v78, v78, v79
	v_cvt_pk_bf16_f32 v79, v84, v85
	ds_write_b64 v200, v[78:79] offset:64
	v_pk_mul_f32 v[78:79], v[136:137], v[64:65]
	v_pk_mul_f32 v[84:85], v[136:137], v[66:67]
	v_cvt_pk_bf16_f32 v78, v78, v79
	v_cvt_pk_bf16_f32 v79, v84, v85
	ds_write_b64 v200, v[78:79] offset:96
	s_waitcnt lgkmcnt(0)
	ds_read_b128 v[204:207], v201
	ds_read_b128 v[208:211], v201 offset:1152
	v_lshl_add_u64 v[212:213], v[76:77], 0, v[202:203]
	v_lshl_add_u64 v[214:215], v[212:213], 0, s[100:101]
	s_waitcnt lgkmcnt(0)
	global_store_dwordx4 v[212:213], v[204:207], off offset:256 sc1
	global_store_dwordx4 v[214:215], v[208:211], off offset:256 sc1
	s_and_saveexec_b64 s[52:53], s[88:89]
	s_cbranch_execz .LBB0_224
	v_cmp_eq_u32_e32 vcc, s18, v158
	v_mov_b32_e32 v151, v199
	v_mov_b32_e32 v149, v199
	v_cndmask_b32_e32 v198, 0, v250, vcc
	v_lshl_add_u64 v[76:77], s[34:35], 0, v[198:199]
	v_lshl_add_u64 v[76:77], v[76:77], 0, v[92:93]
	v_lshl_add_u64 v[76:77], v[76:77], 0, v[150:151]
	v_lshl_add_u64 v[76:77], v[76:77], 0, v[148:149]
	ds_write_b128 v216, v[80:83]
	ds_write_b128 v216, v[72:75] offset:64
	ds_write_b128 v216, v[68:71] offset:128
	ds_write_b128 v216, v[64:67] offset:192
	ds_read_b128 v[220:223], v217
	ds_read_b128 v[224:227], v217 offset:1088
	ds_read_b128 v[228:231], v217 offset:2176
	ds_read_b128 v[232:235], v217 offset:3264
	v_lshl_add_u64 v[242:243], v[76:77], 0, v[238:239]
	v_lshl_add_u64 v[218:219], v[76:77], 0, v[236:237]
	s_waitcnt lgkmcnt(0)
	global_store_dwordx4 v[218:219], v[220:223], off nt
	global_store_dwordx4 v[218:219], v[224:227], off offset:2048 nt
	global_store_dwordx4 v[242:243], v[228:231], off nt
	global_store_dwordx4 v[242:243], v[232:235], off offset:2048 nt

.LBB0_226:
	s_or_b64 exec, exec, s[12:13]
	v_mad_i64_i32 v[30:31], s[12:13], v66, s62, v[156:157]
	v_pk_mul_f32 v[40:41], v[154:155], v[32:33]
	v_pk_mul_f32 v[42:43], v[154:155], v[34:35]
	v_lshl_add_u64 v[38:39], v[152:153], 1, v[30:31]
	v_cvt_pk_bf16_f32 v40, v40, v41
	v_cvt_pk_bf16_f32 v41, v42, v43
	ds_write_b64 v200, v[40:41]
	v_pk_mul_f32 v[40:41], v[154:155], v[24:25]
	v_pk_mul_f32 v[42:43], v[154:155], v[26:27]
	v_cvt_pk_bf16_f32 v40, v40, v41
	v_cvt_pk_bf16_f32 v41, v42, v43
	ds_write_b64 v200, v[40:41] offset:32
	v_pk_mul_f32 v[40:41], v[154:155], v[20:21]
	v_pk_mul_f32 v[42:43], v[154:155], v[22:23]
	v_or_b32_e32 v28, s23, v65
	v_cvt_pk_bf16_f32 v40, v40, v41
	v_cvt_pk_bf16_f32 v41, v42, v43
	v_ashrrev_i32_e32 v29, 31, v28
	ds_write_b64 v200, v[40:41] offset:64
	v_pk_mul_f32 v[40:41], v[154:155], v[16:17]
	v_pk_mul_f32 v[42:43], v[154:155], v[18:19]
	v_lshlrev_b64 v[28:29], 9, v[28:29]
	v_cvt_pk_bf16_f32 v40, v40, v41
	v_cvt_pk_bf16_f32 v41, v42, v43
	ds_write_b64 v200, v[40:41] offset:96
	s_waitcnt lgkmcnt(0)
	ds_read_b128 v[204:207], v201
	ds_read_b128 v[208:211], v201 offset:1152
	v_lshl_add_u64 v[212:213], v[38:39], 0, v[202:203]
	v_lshl_add_u64 v[214:215], v[212:213], 0, s[100:101]
	s_waitcnt lgkmcnt(0)
	global_store_dwordx4 v[212:213], v[204:207], off sc1
	global_store_dwordx4 v[214:215], v[208:211], off sc1
	s_and_saveexec_b64 s[12:13], s[92:93]
	s_cbranch_execz .LBB0_228
	v_cmp_eq_u32_e32 vcc, s18, v168
	v_mov_b32_e32 v151, v199
	v_mov_b32_e32 v149, v199
	v_cndmask_b32_e32 v198, 0, v250, vcc
	v_lshl_add_u64 v[38:39], s[34:35], 0, v[198:199]
	v_lshl_add_u64 v[38:39], v[38:39], 0, v[28:29]
	v_lshl_add_u64 v[38:39], v[38:39], 0, v[150:151]
	v_lshl_add_u64 v[38:39], v[38:39], 0, v[148:149]
	ds_write_b128 v216, v[32:35]
	ds_write_b128 v216, v[24:27] offset:64
	ds_write_b128 v216, v[20:23] offset:128
	ds_write_b128 v216, v[16:19] offset:192
	ds_read_b128 v[220:223], v217
	ds_read_b128 v[224:227], v217 offset:1088
	ds_read_b128 v[228:231], v217 offset:2176
	ds_read_b128 v[232:235], v217 offset:3264
	v_lshl_add_u64 v[242:243], v[38:39], 0, v[238:239]
	v_lshl_add_u64 v[218:219], v[38:39], 0, v[236:237]
	s_waitcnt lgkmcnt(0)
	global_store_dwordx4 v[218:219], v[220:223], off nt
	global_store_dwordx4 v[218:219], v[224:227], off offset:2048 nt
	global_store_dwordx4 v[242:243], v[228:231], off nt
	global_store_dwordx4 v[242:243], v[232:235], off offset:2048 nt

.LBB0_230:
	s_or_b64 exec, exec, s[12:13]
	v_pk_mul_f32 v[14:15], v[136:137], v[16:17]
	v_pk_mul_f32 v[20:21], v[136:137], v[18:19]
	v_lshl_add_u64 v[12:13], v[138:139], 1, v[30:31]
	v_cvt_pk_bf16_f32 v14, v14, v15
	v_cvt_pk_bf16_f32 v15, v20, v21
	ds_write_b64 v200, v[14:15]
	v_pk_mul_f32 v[14:15], v[136:137], v[8:9]
	v_pk_mul_f32 v[20:21], v[136:137], v[10:11]
	v_cvt_pk_bf16_f32 v14, v14, v15
	v_cvt_pk_bf16_f32 v15, v20, v21
	ds_write_b64 v200, v[14:15] offset:32
	v_pk_mul_f32 v[14:15], v[136:137], v[4:5]
	v_pk_mul_f32 v[20:21], v[136:137], v[6:7]
	v_cvt_pk_bf16_f32 v14, v14, v15
	v_cvt_pk_bf16_f32 v15, v20, v21
	ds_write_b64 v200, v[14:15] offset:64
	v_pk_mul_f32 v[14:15], v[136:137], v[0:1]
	v_pk_mul_f32 v[20:21], v[136:137], v[2:3]
	v_cvt_pk_bf16_f32 v14, v14, v15
	v_cvt_pk_bf16_f32 v15, v20, v21
	ds_write_b64 v200, v[14:15] offset:96
	s_waitcnt lgkmcnt(0)
	ds_read_b128 v[204:207], v201
	ds_read_b128 v[208:211], v201 offset:1152
	v_lshl_add_u64 v[212:213], v[12:13], 0, v[202:203]
	v_lshl_add_u64 v[214:215], v[212:213], 0, s[100:101]
	s_waitcnt lgkmcnt(0)
	global_store_dwordx4 v[212:213], v[204:207], off offset:256 sc1
	global_store_dwordx4 v[214:215], v[208:211], off offset:256 sc1
	s_and_saveexec_b64 s[12:13], s[88:89]
	s_cbranch_execz .LBB0_189
	v_cmp_eq_u32_e32 vcc, s18, v158
	v_mov_b32_e32 v151, v199
	v_mov_b32_e32 v149, v199
	v_cndmask_b32_e32 v198, 0, v250, vcc
	v_lshl_add_u64 v[12:13], s[34:35], 0, v[198:199]
	v_lshl_add_u64 v[12:13], v[12:13], 0, v[28:29]
	v_lshl_add_u64 v[12:13], v[12:13], 0, v[150:151]
	v_lshl_add_u64 v[12:13], v[12:13], 0, v[148:149]
	ds_write_b128 v216, v[16:19]
	ds_write_b128 v216, v[8:11] offset:64
	ds_write_b128 v216, v[4:7] offset:128
	ds_write_b128 v216, v[0:3] offset:192
	ds_read_b128 v[220:223], v217
	ds_read_b128 v[224:227], v217 offset:1088
	ds_read_b128 v[228:231], v217 offset:2176
	ds_read_b128 v[232:235], v217 offset:3264
	v_lshl_add_u64 v[242:243], v[12:13], 0, v[238:239]
	v_lshl_add_u64 v[218:219], v[12:13], 0, v[236:237]
	s_waitcnt lgkmcnt(0)
	global_store_dwordx4 v[218:219], v[220:223], off nt
	global_store_dwordx4 v[218:219], v[224:227], off offset:2048 nt
	global_store_dwordx4 v[242:243], v[228:231], off nt
	global_store_dwordx4 v[242:243], v[232:235], off offset:2048 nt
	s_branch .LBB0_189
